# plus FFN-down phases (P2,P16) process odd row-groups first so the A operand written last by the previous phase is read while MALL-resident
# baseline (speedup 1.0000x reference)
; #define LAS __attribute__((address_space(3)))
;     __device__ bool next(int i, Unit& u) const {
;         const long L = (long)i * G + c; if (L >= nwg) return false;
;         int wgid = (int)L; { const int q = nwg / NXCD, r = nwg % NXCD, xcd = wgid % NXCD, off = wgid / NXCD; wgid = (xcd < r ? xcd * (q + 1) : r * (q + 1) + (xcd - r) * q) + off; }
;         const int nig = WGM * nN, gid = wgid / nig, fm = gid * WGM, gsz = (nM - fm) < WGM ? (nM - fm) : WGM;
;         u.pm = fm + ((wgid % nig) % gsz); u.pn = (wgid % nig) / gsz; return true;
; __device__ __forceinline__ void* ldptr(ldsp lds, int idx) {
;     volatile LAS unsigned* t = (volatile LAS unsigned*)(lds + 143360) + 2 * idx;
;     const unsigned lo = __builtin_amdgcn_readfirstlane(t[0]), hi = __builtin_amdgcn_readfirstlane(t[1]);
;     return (void*)(((unsigned long long)hi << 32) | lo);
.LBB0_201:
	v_writelane_b32 v254, s58, 4
	s_nop 1
	v_writelane_b32 v254, s59, 5
	s_or_b64 exec, exec, s[2:3]
	s_add_i32 s17, 0, 0x23090
	v_mov_b32_e32 v0, s17
	s_waitcnt lgkmcnt(0)
	s_barrier
	ds_read_b32 v0, v0
	s_add_i32 s0, 0, 0x23000
	v_mov_b32_e32 v1, s0
	s_add_i32 s0, 0, 0x23004
	s_add_i32 s42, 0, 0x23094
	v_mov_b32_e32 v2, s0
	s_add_i32 s0, 0, 0x23088
	s_waitcnt lgkmcnt(0)
	v_readfirstlane_b32 s8, v0
	v_mov_b32_e32 v0, s42
	v_mov_b32_e32 v3, s0
	s_add_i32 s0, 0, 0x2308c
	ds_read_b32 v0, v0
	v_mov_b32_e32 v4, s0
	ds_read_b32 v1, v1
	ds_read_b32 v2, v2
	ds_read_b32 v3, v3
	ds_read_b32 v4, v4
	s_waitcnt lgkmcnt(0)
	v_readfirstlane_b32 s9, v0
	v_mbcnt_lo_u32_b32 v8, -1, 0
	v_mbcnt_hi_u32_b32 v8, -1, v8
	s_cmpk_lt_i32 s93, 0x400
	v_or_b32_e32 v0, s59, v8
	v_readfirstlane_b32 s2, v1
	v_readfirstlane_b32 s3, v2
	v_readfirstlane_b32 s6, v3
	v_readfirstlane_b32 s7, v4
	s_cselect_b64 s[58:59], -1, 0
	s_cmpk_gt_i32 s93, 0x3ff
	v_readfirstlane_b32 s4, v0
	s_cbranch_scc1 .LBB0_229
	s_ashr_i32 s43, s93, 31
	s_lshr_b32 s0, s43, 29
	s_add_i32 s10, s93, s0
	s_and_b32 s0, s10, -8
	s_sub_i32 s11, s93, s0
	s_lshl_b32 s99, s33, 1
	s_add_i32 s10, s10, s99
	s_cmp_gt_i32 s11, -1
	s_cbranch_scc0 .LBB0_204
	s_lshl_b32 s5, s11, 7
	s_cbranch_execz .LBB0_205
	s_branch .LBB0_206

;     __device__ bool next(int i, Unit& u) const {
;         const long L = (long)i * G + c; if (L >= nwg) return false;
;         int wgid = (int)L; { const int q = nwg / NXCD, r = nwg % NXCD, xcd = wgid % NXCD, off = wgid / NXCD; wgid = (xcd < r ? xcd * (q + 1) : r * (q + 1) + (xcd - r) * q) + off; }
; template <class Epi>
; __device__ __forceinline__ void gemm_phase(ldsp lds, const Gemm g, const StaticOrder& S, const Epi& E, int wave0) {
;     ...
;         const bool has_next = S.next(ui + 1, nxt);
.LBB0_211:
	s_add_i32 s53, s53, 1
	s_xor_b32 s99, s53, 2
	s_mul_i32 s0, s99, s60
	s_mul_hi_u32 s1, s99, s33
	s_add_i32 s1, s1, s0
	s_mul_i32 s0, s99, s33
	s_add_u32 s0, s0, s93
	s_addc_u32 s1, s1, s43
	v_cmp_gt_i64_e32 vcc, s[0:1], v[142:143]
	v_cmp_lt_i64_e64 s[4:5], s[0:1], v[140:141]
	s_cbranch_vccnz .LBB0_217
	s_ashr_i32 s1, s0, 31
	s_lshr_b32 s1, s1, 29
	s_add_i32 s30, s0, s1
	s_and_b32 s1, s30, -8
	s_sub_i32 s31, s0, s1
	s_cmp_gt_i32 s31, -1
	s_mov_b64 s[0:1], -1
	s_cbranch_scc0 .LBB0_214
	s_lshl_b32 s38, s31, 7
	s_mov_b64 s[0:1], 0

; #define LAS __attribute__((address_space(3)))
;     __device__ bool next(int i, Unit& u) const {
;         const long L = (long)i * G + c; if (L >= nwg) return false;
;         int wgid = (int)L; { const int q = nwg / NXCD, r = nwg % NXCD, xcd = wgid % NXCD, off = wgid / NXCD; wgid = (xcd < r ? xcd * (q + 1) : r * (q + 1) + (xcd - r) * q) + off; }
;         const int nig = WGM * nN, gid = wgid / nig, fm = gid * WGM, gsz = (nM - fm) < WGM ? (nM - fm) : WGM;
;         u.pm = fm + ((wgid % nig) % gsz); u.pn = (wgid % nig) / gsz; return true;
; __device__ __forceinline__ void* ldptr(ldsp lds, int idx) {
;     volatile LAS unsigned* t = (volatile LAS unsigned*)(lds + 143360) + 2 * idx;
;     const unsigned lo = __builtin_amdgcn_readfirstlane(t[0]), hi = __builtin_amdgcn_readfirstlane(t[1]);
;     return (void*)(((unsigned long long)hi << 32) | lo);
.LBB0_940:
	s_or_b64 exec, exec, s[2:3]
	s_add_i32 s15, 0, 0x23090
	s_add_i32 s0, 0, 0x23088
	v_mov_b32_e32 v0, s15
	s_add_i32 s42, 0, 0x23094
	v_mov_b32_e32 v2, s0
	s_add_i32 s0, 0, 0x2308c
	s_waitcnt lgkmcnt(0)
	s_barrier
	ds_read_b32 v0, v0
	v_mov_b32_e32 v1, s42
	v_mov_b32_e32 v3, s0
	ds_read_b32 v1, v1
	ds_read_b32 v2, v2
	ds_read_b32 v3, v3
	v_readlane_b32 s0, v254, 9
	s_waitcnt lgkmcnt(0)
	v_readfirstlane_b32 s5, v0
	v_mbcnt_lo_u32_b32 v8, -1, 0
	v_mbcnt_hi_u32_b32 v8, -1, v8
	v_readlane_b32 s1, v254, 10
	v_or_b32_e32 v0, s59, v8
	v_readfirstlane_b32 s9, v1
	v_readfirstlane_b32 s2, v2
	v_readfirstlane_b32 s3, v3
	s_and_b64 vcc, exec, s[0:1]
	v_readfirstlane_b32 s4, v0
	s_cbranch_vccnz .LBB0_968
	s_ashr_i32 s43, s93, 31
	s_lshr_b32 s0, s43, 29
	s_add_i32 s7, s93, s0
	s_and_b32 s0, s7, -8
	s_sub_i32 s8, s93, s0
	s_lshl_b32 s99, s33, 1
	s_add_i32 s7, s7, s99
	s_cmp_gt_i32 s8, -1
	s_cbranch_scc0 .LBB0_943
	s_lshl_b32 s6, s8, 7
	s_cbranch_execz .LBB0_944
	s_branch .LBB0_945

;     __device__ bool next(int i, Unit& u) const {
;         const long L = (long)i * G + c; if (L >= nwg) return false;
;         int wgid = (int)L; { const int q = nwg / NXCD, r = nwg % NXCD, xcd = wgid % NXCD, off = wgid / NXCD; wgid = (xcd < r ? xcd * (q + 1) : r * (q + 1) + (xcd - r) * q) + off; }
; template <class Epi>
; __device__ __forceinline__ void gemm_phase(ldsp lds, const Gemm g, const StaticOrder& S, const Epi& E, int wave0) {
;     ...
;         const bool has_next = S.next(ui + 1, nxt);
.LBB0_950:
	s_add_i32 s53, s53, 1
	s_xor_b32 s99, s53, 2
	s_mul_i32 s0, s99, s58
	s_mul_hi_u32 s1, s99, s33
	s_add_i32 s1, s1, s0
	s_mul_i32 s0, s99, s33
	s_add_u32 s0, s0, s93
	s_addc_u32 s1, s1, s43
	v_cmp_gt_i64_e32 vcc, s[0:1], v[142:143]
	v_cmp_lt_i64_e64 s[4:5], s[0:1], v[140:141]
	s_cbranch_vccnz .LBB0_956
	s_ashr_i32 s1, s0, 31
	s_lshr_b32 s1, s1, 29
	s_add_i32 s30, s0, s1
	s_and_b32 s1, s30, -8
	s_sub_i32 s31, s0, s1
	s_cmp_gt_i32 s31, -1
	s_mov_b64 s[0:1], -1
	s_cbranch_scc0 .LBB0_953
	s_lshl_b32 s38, s31, 7
	s_mov_b64 s[0:1], 0
